# v34: v33 + 64-byte alignment of the attention K/V loop head and the in-proj K-loop head
# speedup vs baseline: 1.0087x; 1.0019x over previous
.LBB0_258:
	s_and_b64 s[26:27], s[56:57], exec
	s_cselect_b32 s6, s53, s11
	s_cselect_b32 s36, s52, s10
	s_cselect_b32 s37, s55, s15
	s_cselect_b32 s40, s54, s14
	s_add_u32 s10, s10, 0x40080
	s_addc_u32 s11, s11, 0
	s_add_u32 s41, s14, 0x100
	v_mov_b32_e32 v2, 0
	s_addc_u32 s43, s15, 0
	s_mov_b32 s49, -2
	v_mov_b32_e32 v3, v2
	v_mov_b32_e32 v4, v2
	v_mov_b32_e32 v5, v2
	v_mov_b32_e32 v6, v2
	v_mov_b32_e32 v7, v2
	v_mov_b32_e32 v8, v2
	v_mov_b32_e32 v9, v2
	v_mov_b32_e32 v18, v2
	v_mov_b32_e32 v19, v2
	v_mov_b32_e32 v20, v2
	v_mov_b32_e32 v21, v2
	v_mov_b32_e32 v22, v2
	v_mov_b32_e32 v23, v2
	v_mov_b32_e32 v24, v2
	v_mov_b32_e32 v25, v2
	v_mov_b32_e32 v34, v2
	v_mov_b32_e32 v35, v2
	v_mov_b32_e32 v36, v2
	v_mov_b32_e32 v37, v2
	v_mov_b32_e32 v38, v2
	v_mov_b32_e32 v39, v2
	v_mov_b32_e32 v40, v2
	v_mov_b32_e32 v41, v2
	v_mov_b32_e32 v50, v2
	v_mov_b32_e32 v51, v2
	v_mov_b32_e32 v52, v2
	v_mov_b32_e32 v53, v2
	v_mov_b32_e32 v54, v2
	v_mov_b32_e32 v55, v2
	v_mov_b32_e32 v56, v2
	v_mov_b32_e32 v57, v2
	v_mov_b32_e32 v10, v2
	v_mov_b32_e32 v11, v2
	v_mov_b32_e32 v12, v2
	v_mov_b32_e32 v13, v2
	v_mov_b32_e32 v14, v2
	v_mov_b32_e32 v15, v2
	v_mov_b32_e32 v16, v2
	v_mov_b32_e32 v17, v2
	v_mov_b32_e32 v26, v2
	v_mov_b32_e32 v27, v2
	v_mov_b32_e32 v28, v2
	v_mov_b32_e32 v29, v2
	v_mov_b32_e32 v30, v2
	v_mov_b32_e32 v31, v2
	v_mov_b32_e32 v32, v2
	v_mov_b32_e32 v33, v2
	v_mov_b32_e32 v42, v2
	v_mov_b32_e32 v43, v2
	v_mov_b32_e32 v44, v2
	v_mov_b32_e32 v45, v2
	v_mov_b32_e32 v46, v2
	v_mov_b32_e32 v47, v2
	v_mov_b32_e32 v48, v2
	v_mov_b32_e32 v49, v2
	v_mov_b32_e32 v58, v2
	v_mov_b32_e32 v59, v2
	v_mov_b32_e32 v60, v2
	v_mov_b32_e32 v61, v2
	v_mov_b32_e32 v62, v2
	v_mov_b32_e32 v63, v2
	v_mov_b32_e32 v64, v2
	v_mov_b32_e32 v65, v2
	v_mov_b32_e32 v66, v2
	v_mov_b32_e32 v67, v2
	v_mov_b32_e32 v68, v2
	v_mov_b32_e32 v69, v2
	v_mov_b32_e32 v70, v2
	v_mov_b32_e32 v71, v2
	v_mov_b32_e32 v72, v2
	v_mov_b32_e32 v73, v2
	v_mov_b32_e32 v82, v2
	v_mov_b32_e32 v83, v2
	v_mov_b32_e32 v84, v2
	v_mov_b32_e32 v85, v2
	v_mov_b32_e32 v86, v2
	v_mov_b32_e32 v87, v2
	v_mov_b32_e32 v88, v2
	v_mov_b32_e32 v89, v2
	v_mov_b32_e32 v98, v2
	v_mov_b32_e32 v99, v2
	v_mov_b32_e32 v100, v2
	v_mov_b32_e32 v101, v2
	v_mov_b32_e32 v102, v2
	v_mov_b32_e32 v103, v2
	v_mov_b32_e32 v104, v2
	v_mov_b32_e32 v105, v2
	v_mov_b32_e32 v114, v2
	v_mov_b32_e32 v115, v2
	v_mov_b32_e32 v116, v2
	v_mov_b32_e32 v117, v2
	v_mov_b32_e32 v118, v2
	v_mov_b32_e32 v119, v2
	v_mov_b32_e32 v120, v2
	v_mov_b32_e32 v121, v2
	v_mov_b32_e32 v74, v2
	v_mov_b32_e32 v75, v2
	v_mov_b32_e32 v76, v2
	v_mov_b32_e32 v77, v2
	v_mov_b32_e32 v78, v2
	v_mov_b32_e32 v79, v2
	v_mov_b32_e32 v80, v2
	v_mov_b32_e32 v81, v2
	v_mov_b32_e32 v90, v2
	v_mov_b32_e32 v91, v2
	v_mov_b32_e32 v92, v2
	v_mov_b32_e32 v93, v2
	v_mov_b32_e32 v94, v2
	v_mov_b32_e32 v95, v2
	v_mov_b32_e32 v96, v2
	v_mov_b32_e32 v97, v2
	v_mov_b32_e32 v106, v2
	v_mov_b32_e32 v107, v2
	v_mov_b32_e32 v108, v2
	v_mov_b32_e32 v109, v2
	v_mov_b32_e32 v110, v2
	v_mov_b32_e32 v111, v2
	v_mov_b32_e32 v112, v2
	v_mov_b32_e32 v113, v2
	v_mov_b32_e32 v122, v2
	v_mov_b32_e32 v123, v2
	v_mov_b32_e32 v124, v2
	v_mov_b32_e32 v125, v2
	v_mov_b32_e32 v126, v2
	v_mov_b32_e32 v127, v2
	v_mov_b32_e32 v128, v2
	v_mov_b32_e32 v129, v2
	s_cmp_eq_u32 s73, 1
	s_cbranch_scc1 .LBB0_259
	s_add_u32 s14, s10, 0xfffc0080
	s_addc_u32 s15, s11, -1
	s_cmp_eq_u32 s49, 12
	s_cselect_b32 s27, s6, s15
	s_cselect_b32 s26, s36, s14
	v_add_u32_e32 v146, s33, v154
	s_cselect_b32 s15, s37, s43
	s_cselect_b32 s14, s40, s41
	s_add_i32 s51, 0, 0x14000
	ds_read_b128 v[142:145], v146
	ds_read_b128 v[158:161], v146 offset:1024
	ds_read_b128 v[162:165], v146 offset:2048
	ds_read_b128 v[166:169], v146 offset:3072
	v_add_u32_e32 v146, s51, v154
	ds_read_b128 v[170:173], v146
	ds_read_b128 v[174:177], v146 offset:1024
	ds_read_b128 v[178:181], v146 offset:2048
	ds_read_b128 v[182:185], v146 offset:3072
	v_lshl_add_u64 v[146:147], s[10:11], 0, v[138:139]
	s_add_i32 m0, s67, 0xc000
	ds_read_b128 v[186:189], v156
	ds_read_b128 v[190:193], v156 offset:1024
	ds_read_b128 v[194:197], v156 offset:2048
	ds_read_b128 v[198:201], v156 offset:3072
	ds_read_b128 v[202:205], v156 offset:4096
	ds_read_b128 v[206:209], v156 offset:5120
	ds_read_b128 v[210:213], v156 offset:6144
	ds_read_b128 v[214:217], v156 offset:7168
	v_lshl_add_u64 v[146:147], s[10:11], 0, v[140:141]
	s_add_i32 m0, s67, 0xe000
	s_nop 0
	s_waitcnt vmcnt(24)
	s_waitcnt lgkmcnt(0)
	s_barrier
	s_setprio 1
	s_waitcnt lgkmcnt(0)
	v_mfma_f32_16x16x32_bf16 v[126:129], v[142:145], v[186:189], v[126:129]
	v_mfma_f32_16x16x32_bf16 v[122:125], v[162:165], v[186:189], v[122:125]
	v_mfma_f32_16x16x32_bf16 v[110:113], v[142:145], v[194:197], v[110:113]
	v_mfma_f32_16x16x32_bf16 v[106:109], v[162:165], v[194:197], v[106:109]
	v_mfma_f32_16x16x32_bf16 v[94:97], v[142:145], v[202:205], v[94:97]
	v_mfma_f32_16x16x32_bf16 v[90:93], v[162:165], v[202:205], v[90:93]
	v_mfma_f32_16x16x32_bf16 v[78:81], v[142:145], v[210:213], v[78:81]
	v_mfma_f32_16x16x32_bf16 v[74:77], v[162:165], v[210:213], v[74:77]
	v_mfma_f32_16x16x32_bf16 v[126:129], v[158:161], v[190:193], v[126:129]
	v_mfma_f32_16x16x32_bf16 v[122:125], v[166:169], v[190:193], v[122:125]
	v_mfma_f32_16x16x32_bf16 v[110:113], v[158:161], v[198:201], v[110:113]
	v_mfma_f32_16x16x32_bf16 v[106:109], v[166:169], v[198:201], v[106:109]
	v_mfma_f32_16x16x32_bf16 v[94:97], v[158:161], v[206:209], v[94:97]
	v_mfma_f32_16x16x32_bf16 v[90:93], v[166:169], v[206:209], v[90:93]
	v_mfma_f32_16x16x32_bf16 v[78:81], v[158:161], v[214:217], v[78:81]
	v_mfma_f32_16x16x32_bf16 v[74:77], v[166:169], v[214:217], v[74:77]
	s_setprio 0
	s_setprio 1
	v_mfma_f32_16x16x32_bf16 v[118:121], v[170:173], v[186:189], v[118:121]
	v_mfma_f32_16x16x32_bf16 v[114:117], v[178:181], v[186:189], v[114:117]
	v_mfma_f32_16x16x32_bf16 v[102:105], v[170:173], v[194:197], v[102:105]
	v_mfma_f32_16x16x32_bf16 v[98:101], v[178:181], v[194:197], v[98:101]
	v_mfma_f32_16x16x32_bf16 v[86:89], v[170:173], v[202:205], v[86:89]
	v_mfma_f32_16x16x32_bf16 v[82:85], v[178:181], v[202:205], v[82:85]
	v_mfma_f32_16x16x32_bf16 v[70:73], v[170:173], v[210:213], v[70:73]
	v_mfma_f32_16x16x32_bf16 v[66:69], v[178:181], v[210:213], v[66:69]
	v_mfma_f32_16x16x32_bf16 v[118:121], v[174:177], v[190:193], v[118:121]
	v_mfma_f32_16x16x32_bf16 v[114:117], v[182:185], v[190:193], v[114:117]
	v_mfma_f32_16x16x32_bf16 v[102:105], v[174:177], v[198:201], v[102:105]
	v_mfma_f32_16x16x32_bf16 v[98:101], v[182:185], v[198:201], v[98:101]
	v_mfma_f32_16x16x32_bf16 v[86:89], v[174:177], v[206:209], v[86:89]
	v_mfma_f32_16x16x32_bf16 v[82:85], v[182:185], v[206:209], v[82:85]
	v_mfma_f32_16x16x32_bf16 v[70:73], v[174:177], v[214:217], v[70:73]
	v_mfma_f32_16x16x32_bf16 v[66:69], v[182:185], v[214:217], v[66:69]
	s_setprio 0
	s_barrier
	s_add_i32 s58, s33, s66
	v_lshl_add_u64 v[146:147], s[14:15], 0, v[132:133]
	s_mov_b32 m0, s58
	ds_read_b128 v[186:189], v156 offset:16384
	ds_read_b128 v[190:193], v156 offset:17408
	ds_read_b128 v[194:197], v156 offset:18432
	ds_read_b128 v[198:201], v156 offset:19456
	ds_read_b128 v[202:205], v156 offset:20480
	ds_read_b128 v[206:209], v156 offset:21504
	ds_read_b128 v[210:213], v156 offset:22528
	ds_read_b128 v[214:217], v156 offset:23552
	global_load_lds_dwordx4 v[146:147], off
	s_add_i32 m0, s58, 0x2000
	s_add_u32 s58, s14, 0x40000
	v_lshl_add_u64 v[148:149], s[14:15], 0, v[136:137]
	s_addc_u32 s59, s15, 0
	s_add_i32 s51, s51, s66
	global_load_lds_dwordx4 v[148:149], off
	v_lshl_add_u64 v[150:151], s[58:59], 0, v[132:133]
	s_mov_b32 m0, s51
	v_lshl_add_u64 v[152:153], s[26:27], 0, v[134:135]
	global_load_lds_dwordx4 v[150:151], off
	v_lshl_add_u64 v[150:151], s[58:59], 0, v[136:137]
	s_add_i32 m0, s51, 0x2000
	s_nop 0
	global_load_lds_dwordx4 v[150:151], off
	v_lshl_add_u64 v[150:151], s[26:27], 0, v[130:131]
	s_mov_b32 m0, s67
	s_nop 0
	global_load_lds_dwordx4 v[150:151], off
	s_mov_b32 m0, s68
	s_nop 0
	global_load_lds_dwordx4 v[152:153], off
	s_waitcnt vmcnt(24)
	s_waitcnt lgkmcnt(0)
	s_barrier
	s_setprio 1
	s_waitcnt lgkmcnt(0)
	v_mfma_f32_16x16x32_bf16 v[62:65], v[142:145], v[186:189], v[62:65]
	v_mfma_f32_16x16x32_bf16 v[58:61], v[162:165], v[186:189], v[58:61]
	v_mfma_f32_16x16x32_bf16 v[46:49], v[142:145], v[194:197], v[46:49]
	v_mfma_f32_16x16x32_bf16 v[42:45], v[162:165], v[194:197], v[42:45]
	v_mfma_f32_16x16x32_bf16 v[30:33], v[142:145], v[202:205], v[30:33]
	v_mfma_f32_16x16x32_bf16 v[26:29], v[162:165], v[202:205], v[26:29]
	v_mfma_f32_16x16x32_bf16 v[14:17], v[142:145], v[210:213], v[14:17]
	v_mfma_f32_16x16x32_bf16 v[10:13], v[162:165], v[210:213], v[10:13]
	v_mfma_f32_16x16x32_bf16 v[62:65], v[158:161], v[190:193], v[62:65]
	v_mfma_f32_16x16x32_bf16 v[58:61], v[166:169], v[190:193], v[58:61]
	v_mfma_f32_16x16x32_bf16 v[46:49], v[158:161], v[198:201], v[46:49]
	v_mfma_f32_16x16x32_bf16 v[42:45], v[166:169], v[198:201], v[42:45]
	v_mfma_f32_16x16x32_bf16 v[30:33], v[158:161], v[206:209], v[30:33]
	v_mfma_f32_16x16x32_bf16 v[26:29], v[166:169], v[206:209], v[26:29]
	v_mfma_f32_16x16x32_bf16 v[14:17], v[158:161], v[214:217], v[14:17]
	v_mfma_f32_16x16x32_bf16 v[10:13], v[166:169], v[214:217], v[10:13]
	s_setprio 0
	s_setprio 1
	v_mfma_f32_16x16x32_bf16 v[54:57], v[170:173], v[186:189], v[54:57]
	v_mfma_f32_16x16x32_bf16 v[50:53], v[178:181], v[186:189], v[50:53]
	v_mfma_f32_16x16x32_bf16 v[38:41], v[170:173], v[194:197], v[38:41]
	v_mfma_f32_16x16x32_bf16 v[34:37], v[178:181], v[194:197], v[34:37]
	v_mfma_f32_16x16x32_bf16 v[22:25], v[170:173], v[202:205], v[22:25]
	v_mfma_f32_16x16x32_bf16 v[18:21], v[178:181], v[202:205], v[18:21]
	v_mfma_f32_16x16x32_bf16 v[6:9], v[170:173], v[210:213], v[6:9]
	v_mfma_f32_16x16x32_bf16 v[2:5], v[178:181], v[210:213], v[2:5]
	v_mfma_f32_16x16x32_bf16 v[54:57], v[174:177], v[190:193], v[54:57]
	v_mfma_f32_16x16x32_bf16 v[50:53], v[182:185], v[190:193], v[50:53]
	v_mfma_f32_16x16x32_bf16 v[38:41], v[174:177], v[198:201], v[38:41]
	v_mfma_f32_16x16x32_bf16 v[34:37], v[182:185], v[198:201], v[34:37]
	v_mfma_f32_16x16x32_bf16 v[22:25], v[174:177], v[206:209], v[22:25]
	v_mfma_f32_16x16x32_bf16 v[18:21], v[182:185], v[206:209], v[18:21]
	v_mfma_f32_16x16x32_bf16 v[6:9], v[174:177], v[214:217], v[6:9]
	v_mfma_f32_16x16x32_bf16 v[2:5], v[182:185], v[214:217], v[2:5]
	s_setprio 0
	s_barrier
	s_add_i32 s51, 0, 0x18000
	v_add_u32_e32 v157, s51, v154
	s_add_i32 s58, 0, 0x1c000
	ds_read_b128 v[142:145], v157
	ds_read_b128 v[158:161], v157 offset:1024
	ds_read_b128 v[162:165], v157 offset:2048
	ds_read_b128 v[166:169], v157 offset:3072
	v_add_u32_e32 v157, s58, v154
	ds_read_b128 v[170:173], v157
	ds_read_b128 v[174:177], v157 offset:1024
	ds_read_b128 v[178:181], v157 offset:2048
	ds_read_b128 v[182:185], v157 offset:3072
	s_add_u32 s26, s26, 0x40000
	s_addc_u32 s27, s27, 0
	s_mov_b32 m0, s69
	v_lshl_add_u64 v[218:219], s[26:27], 0, v[130:131]
	ds_read_b128 v[186:189], v156 offset:32768
	ds_read_b128 v[190:193], v156 offset:33792
	ds_read_b128 v[194:197], v156 offset:34816
	ds_read_b128 v[198:201], v156 offset:35840
	ds_read_b128 v[202:205], v156 offset:36864
	ds_read_b128 v[206:209], v156 offset:37888
	ds_read_b128 v[210:213], v156 offset:38912
	ds_read_b128 v[214:217], v156 offset:39936
	global_load_lds_dwordx4 v[218:219], off
	v_lshl_add_u64 v[218:219], s[26:27], 0, v[134:135]
	s_mov_b32 m0, s70
	s_nop 0
	global_load_lds_dwordx4 v[218:219], off
	s_waitcnt vmcnt(24)
	s_waitcnt lgkmcnt(0)
	s_barrier
	s_setprio 1
	s_waitcnt lgkmcnt(0)
	v_mfma_f32_16x16x32_bf16 v[126:129], v[142:145], v[186:189], v[126:129]
	v_mfma_f32_16x16x32_bf16 v[122:125], v[162:165], v[186:189], v[122:125]
	v_mfma_f32_16x16x32_bf16 v[110:113], v[142:145], v[194:197], v[110:113]
	v_mfma_f32_16x16x32_bf16 v[106:109], v[162:165], v[194:197], v[106:109]
	v_mfma_f32_16x16x32_bf16 v[94:97], v[142:145], v[202:205], v[94:97]
	v_mfma_f32_16x16x32_bf16 v[90:93], v[162:165], v[202:205], v[90:93]
	v_mfma_f32_16x16x32_bf16 v[78:81], v[142:145], v[210:213], v[78:81]
	v_mfma_f32_16x16x32_bf16 v[74:77], v[162:165], v[210:213], v[74:77]
	v_mfma_f32_16x16x32_bf16 v[126:129], v[158:161], v[190:193], v[126:129]
	v_mfma_f32_16x16x32_bf16 v[122:125], v[166:169], v[190:193], v[122:125]
	v_mfma_f32_16x16x32_bf16 v[110:113], v[158:161], v[198:201], v[110:113]
	v_mfma_f32_16x16x32_bf16 v[106:109], v[166:169], v[198:201], v[106:109]
	v_mfma_f32_16x16x32_bf16 v[94:97], v[158:161], v[206:209], v[94:97]
	v_mfma_f32_16x16x32_bf16 v[90:93], v[166:169], v[206:209], v[90:93]
	v_mfma_f32_16x16x32_bf16 v[78:81], v[158:161], v[214:217], v[78:81]
	v_mfma_f32_16x16x32_bf16 v[74:77], v[166:169], v[214:217], v[74:77]
	s_setprio 0
	s_setprio 1
	v_mfma_f32_16x16x32_bf16 v[118:121], v[170:173], v[186:189], v[118:121]
	v_mfma_f32_16x16x32_bf16 v[114:117], v[178:181], v[186:189], v[114:117]
	v_mfma_f32_16x16x32_bf16 v[102:105], v[170:173], v[194:197], v[102:105]
	v_mfma_f32_16x16x32_bf16 v[98:101], v[178:181], v[194:197], v[98:101]
	v_mfma_f32_16x16x32_bf16 v[86:89], v[170:173], v[202:205], v[86:89]
	v_mfma_f32_16x16x32_bf16 v[82:85], v[178:181], v[202:205], v[82:85]
	v_mfma_f32_16x16x32_bf16 v[70:73], v[170:173], v[210:213], v[70:73]
	v_mfma_f32_16x16x32_bf16 v[66:69], v[178:181], v[210:213], v[66:69]
	v_mfma_f32_16x16x32_bf16 v[118:121], v[174:177], v[190:193], v[118:121]
	v_mfma_f32_16x16x32_bf16 v[114:117], v[182:185], v[190:193], v[114:117]
	v_mfma_f32_16x16x32_bf16 v[102:105], v[174:177], v[198:201], v[102:105]
	v_mfma_f32_16x16x32_bf16 v[98:101], v[182:185], v[198:201], v[98:101]
	v_mfma_f32_16x16x32_bf16 v[86:89], v[174:177], v[206:209], v[86:89]
	v_mfma_f32_16x16x32_bf16 v[82:85], v[182:185], v[206:209], v[82:85]
	v_mfma_f32_16x16x32_bf16 v[70:73], v[174:177], v[214:217], v[70:73]
	v_mfma_f32_16x16x32_bf16 v[66:69], v[182:185], v[214:217], v[66:69]
	s_setprio 0
	s_barrier
	s_add_i32 s26, s51, s66
	v_lshl_add_u64 v[146:147], v[146:147], 0, s[24:25]
	s_mov_b32 m0, s26
	ds_read_b128 v[186:189], v156 offset:49152
	ds_read_b128 v[190:193], v156 offset:50176
	ds_read_b128 v[194:197], v156 offset:51200
	ds_read_b128 v[198:201], v156 offset:52224
	ds_read_b128 v[202:205], v156 offset:53248
	ds_read_b128 v[206:209], v156 offset:54272
	ds_read_b128 v[210:213], v156 offset:55296
	ds_read_b128 v[214:217], v156 offset:56320
	global_load_lds_dwordx4 v[146:147], off
	s_add_i32 m0, s26, 0x2000
	s_add_u32 s14, s14, 0x40080
	v_lshl_add_u64 v[146:147], v[148:149], 0, s[24:25]
	s_addc_u32 s15, s15, 0
	s_add_i32 s26, s58, s66
	global_load_lds_dwordx4 v[146:147], off
	v_lshl_add_u64 v[146:147], s[14:15], 0, v[132:133]
	s_mov_b32 m0, s26
	s_nop 0
	global_load_lds_dwordx4 v[146:147], off
	v_lshl_add_u64 v[146:147], s[14:15], 0, v[136:137]
	s_add_i32 m0, s26, 0x2000
	s_nop 0
	global_load_lds_dwordx4 v[146:147], off
	v_lshl_add_u64 v[146:147], v[150:151], 0, s[24:25]
	s_mov_b32 m0, s71
	s_nop 0
	global_load_lds_dwordx4 v[146:147], off
	v_lshl_add_u64 v[146:147], v[152:153], 0, s[24:25]
	s_mov_b32 m0, s72
	s_nop 0
	global_load_lds_dwordx4 v[146:147], off
	s_waitcnt vmcnt(8)
	s_waitcnt lgkmcnt(0)
	s_barrier
	s_setprio 1
	s_waitcnt lgkmcnt(0)
	v_mfma_f32_16x16x32_bf16 v[62:65], v[142:145], v[186:189], v[62:65]
	v_mfma_f32_16x16x32_bf16 v[58:61], v[162:165], v[186:189], v[58:61]
	v_mfma_f32_16x16x32_bf16 v[46:49], v[142:145], v[194:197], v[46:49]
	v_mfma_f32_16x16x32_bf16 v[42:45], v[162:165], v[194:197], v[42:45]
	v_mfma_f32_16x16x32_bf16 v[30:33], v[142:145], v[202:205], v[30:33]
	v_mfma_f32_16x16x32_bf16 v[26:29], v[162:165], v[202:205], v[26:29]
	v_mfma_f32_16x16x32_bf16 v[14:17], v[142:145], v[210:213], v[14:17]
	v_mfma_f32_16x16x32_bf16 v[10:13], v[162:165], v[210:213], v[10:13]
	v_mfma_f32_16x16x32_bf16 v[62:65], v[158:161], v[190:193], v[62:65]
	v_mfma_f32_16x16x32_bf16 v[58:61], v[166:169], v[190:193], v[58:61]
	v_mfma_f32_16x16x32_bf16 v[46:49], v[158:161], v[198:201], v[46:49]
	v_mfma_f32_16x16x32_bf16 v[42:45], v[166:169], v[198:201], v[42:45]
	v_mfma_f32_16x16x32_bf16 v[30:33], v[158:161], v[206:209], v[30:33]
	v_mfma_f32_16x16x32_bf16 v[26:29], v[166:169], v[206:209], v[26:29]
	v_mfma_f32_16x16x32_bf16 v[14:17], v[158:161], v[214:217], v[14:17]
	v_mfma_f32_16x16x32_bf16 v[10:13], v[166:169], v[214:217], v[10:13]
	s_setprio 0
	s_setprio 1
	v_mfma_f32_16x16x32_bf16 v[54:57], v[170:173], v[186:189], v[54:57]
	v_mfma_f32_16x16x32_bf16 v[50:53], v[178:181], v[186:189], v[50:53]
	v_mfma_f32_16x16x32_bf16 v[38:41], v[170:173], v[194:197], v[38:41]
	v_mfma_f32_16x16x32_bf16 v[34:37], v[178:181], v[194:197], v[34:37]
	v_mfma_f32_16x16x32_bf16 v[22:25], v[170:173], v[202:205], v[22:25]
	v_mfma_f32_16x16x32_bf16 v[18:21], v[178:181], v[202:205], v[18:21]
	v_mfma_f32_16x16x32_bf16 v[6:9], v[170:173], v[210:213], v[6:9]
	v_mfma_f32_16x16x32_bf16 v[2:5], v[178:181], v[210:213], v[2:5]
	v_mfma_f32_16x16x32_bf16 v[54:57], v[174:177], v[190:193], v[54:57]
	v_mfma_f32_16x16x32_bf16 v[50:53], v[182:185], v[190:193], v[50:53]
	v_mfma_f32_16x16x32_bf16 v[38:41], v[174:177], v[198:201], v[38:41]
	v_mfma_f32_16x16x32_bf16 v[34:37], v[182:185], v[198:201], v[34:37]
	v_mfma_f32_16x16x32_bf16 v[22:25], v[174:177], v[206:209], v[22:25]
	v_mfma_f32_16x16x32_bf16 v[18:21], v[182:185], v[206:209], v[18:21]
	v_mfma_f32_16x16x32_bf16 v[6:9], v[174:177], v[214:217], v[6:9]
	v_mfma_f32_16x16x32_bf16 v[2:5], v[182:185], v[214:217], v[2:5]
	s_setprio 0
	s_barrier
	s_add_i32 s49, s49, 2
	s_add_u32 s10, s10, 0x100
	s_addc_u32 s11, s11, 0
	s_add_u32 s41, s41, 0x100
	s_addc_u32 s43, s43, 0
	.p2align 6

.LBB0_747:
	s_and_b64 vcc, exec, s[10:11]
	s_cbranch_vccz .LBB0_751
	v_mov_b32_e32 v10, v232
	s_load_dwordx8 s[52:59], s[44:45], 0x60
	v_and_b32_e32 v181, 63, v10
	v_readlane_b32 s10, v255, 20
	v_mov_b32_e32 v3, v0
	s_load_dwordx2 s[42:43], s[44:45], 0xb0
	v_or_b32_e32 v2, s10, v181
	v_lshlrev_b64 v[2:3], 2, v[2:3]
	s_waitcnt lgkmcnt(0)
	v_lshl_add_u64 v[4:5], s[52:53], 0, v[2:3]
	global_load_dword v11, v[4:5], off
	v_lshl_add_u64 v[4:5], s[54:55], 0, v[2:3]
	global_load_dword v12, v[4:5], off
	v_lshl_add_u64 v[4:5], s[56:57], 0, v[2:3]
	v_lshl_add_u64 v[2:3], s[58:59], 0, v[2:3]
	global_load_dword v13, v[4:5], off
	global_load_dword v14, v[2:3], off
	s_add_i32 s6, s37, s48
	s_lshl_b32 s14, s36, 7
	s_lshl_b32 s30, s36, 8
	v_readlane_b32 s11, v255, 21
	s_add_u32 s10, s42, s47
	s_addc_u32 s11, s43, s46
	s_add_u32 s36, s10, s30
	s_addc_u32 s37, s11, 0
	s_lshl_b32 s10, s27, 10
	s_or_b32 s10, s14, s10
	s_mul_hi_i32 s11, s10, 0x2200
	s_mulk_i32 s10, 0x2200
	v_ashrrev_i32_e32 v50, 4, v10
	s_add_u32 s10, s42, s10
	v_ashrrev_i32_e32 v51, 31, v50
	v_and_b32_e32 v177, 15, v10
	s_addc_u32 s11, s43, s11
	v_lshlrev_b64 v[52:53], 11, v[50:51]
	s_add_u32 s40, s10, 0xe010000
	v_lshl_add_u64 v[2:3], s[36:37], 0, v[52:53]
	v_lshlrev_b32_e32 v124, 4, v177
	v_mov_b32_e32 v125, v0
	s_addc_u32 s41, s11, 0
	v_lshl_add_u64 v[2:3], v[2:3], 0, v[124:125]
	s_mov_b32 s15, 0x16810000
	v_mov_b64_e32 v[4:5], s[40:41]
	s_movk_i32 s35, 0x2200
	v_add_co_u32_e32 v6, vcc, s15, v2
	v_mad_i64_i32 v[4:5], s[36:37], v50, s35, v[4:5]
	s_nop 0
	v_addc_co_u32_e32 v7, vcc, 0, v3, vcc
	s_mov_b32 s15, 0x16820000
	v_lshl_add_u64 v[4:5], v[4:5], 0, v[124:125]
	global_load_dwordx4 v[18:21], v[6:7], off
	global_load_dwordx4 v[22:25], v[4:5], off
	v_add_co_u32_e32 v6, vcc, s15, v2
	s_mov_b32 s15, 0x44000
	s_nop 0
	v_addc_co_u32_e32 v7, vcc, 0, v3, vcc
	v_add_co_u32_e32 v8, vcc, s15, v4
	s_mov_b32 s15, 0x16830000
	s_nop 0
	v_addc_co_u32_e32 v9, vcc, 0, v5, vcc
	global_load_dwordx4 v[26:29], v[6:7], off
	global_load_dwordx4 v[30:33], v[8:9], off
	v_add_co_u32_e32 v6, vcc, s15, v2
	s_mov_b32 s15, 0x88000
	s_nop 0
	v_addc_co_u32_e32 v7, vcc, 0, v3, vcc
	v_add_co_u32_e32 v8, vcc, s15, v4
	s_mov_b32 s15, 0x16840000
	s_nop 0
	v_addc_co_u32_e32 v9, vcc, 0, v5, vcc
	v_add_co_u32_e32 v2, vcc, s15, v2
	s_mov_b32 s15, 0xcc000
	s_nop 0
	v_addc_co_u32_e32 v3, vcc, 0, v3, vcc
	v_add_co_u32_e32 v4, vcc, s15, v4
	global_load_dwordx4 v[34:37], v[6:7], off
	global_load_dwordx4 v[38:41], v[8:9], off
	v_addc_co_u32_e32 v5, vcc, 0, v5, vcc
	global_load_dwordx4 v[42:45], v[2:3], off
	global_load_dwordx4 v[46:49], v[4:5], off
	v_ashrrev_i32_e32 v4, 2, v10
	v_and_b32_e32 v4, 0xffffffe0, v4
	v_add_u32_e32 v180, s6, v4
	v_ashrrev_i32_e32 v182, 6, v10
	v_and_b32_e32 v179, 1, v182
	v_mov_b32_e32 v55, v0
	v_lshlrev_b32_e32 v54, 7, v179
	s_waitcnt vmcnt(10)
	v_mul_f32_e32 v2, v11, v12
	ds_bpermute_b32 v2, v1, v2
	v_and_b32_e32 v56, 48, v10
	v_mov_b32_e32 v57, v0
	s_waitcnt vmcnt(8)
	v_mul_f32_e32 v3, v13, v14
	ds_bpermute_b32 v3, v1, v3
	s_waitcnt lgkmcnt(1)
	v_fmac_f32_e32 v2, v11, v12
	ds_bpermute_b32 v5, v176, v2
	s_mov_b32 s6, 0x14610000
	s_mov_b64 s[36:37], 0x14610000
	s_waitcnt lgkmcnt(1)
	v_fmac_f32_e32 v3, v13, v14
	ds_bpermute_b32 v6, v176, v3
	s_waitcnt lgkmcnt(1)
	v_add_f32_e32 v4, v2, v5
	v_or_b32_e32 v2, v180, v177
	v_bfe_u32 v178, v10, 4, 2
	v_lshlrev_b32_e32 v51, 2, v50
	s_waitcnt lgkmcnt(0)
	v_add_f32_e32 v5, v3, v6
	ds_bpermute_b32 v6, v175, v4
	ds_bpermute_b32 v7, v175, v5
	v_ashrrev_i32_e32 v3, 31, v2
	v_lshlrev_b64 v[2:3], 11, v[2:3]
	v_lshl_add_u64 v[2:3], s[42:43], 0, v[2:3]
	s_waitcnt lgkmcnt(1)
	v_add_f32_e32 v4, v4, v6
	s_waitcnt lgkmcnt(0)
	v_add_f32_e32 v5, v5, v7
	ds_bpermute_b32 v6, v174, v4
	ds_bpermute_b32 v7, v174, v5
	v_lshl_add_u64 v[2:3], v[2:3], 0, s[30:31]
	v_lshl_add_u64 v[2:3], v[2:3], 0, v[54:55]
	v_lshrrev_b32_e32 v55, 1, v50
	s_waitcnt lgkmcnt(1)
	v_add_f32_e32 v132, v4, v6
	s_waitcnt lgkmcnt(0)
	v_add_f32_e32 v133, v5, v7
	v_lshl_add_u64 v[6:7], v[2:3], 0, v[56:57]
	v_add_co_u32_e32 v4, vcc, s6, v6
	s_mov_b32 s6, 0x14618000
	s_nop 0
	v_addc_co_u32_e32 v5, vcc, 0, v7, vcc
	v_lshl_add_u64 v[2:3], v[6:7], 0, s[36:37]
	v_add_co_u32_e32 v6, vcc, s6, v6
	global_load_dwordx4 v[10:13], v[4:5], off
	s_nop 0
	global_load_dwordx4 v[2:5], v[2:3], off offset:64
	v_addc_co_u32_e32 v7, vcc, 0, v7, vcc
	global_load_dwordx4 v[14:17], v[6:7], off
	s_nop 0
	global_load_dwordx4 v[6:9], v[6:7], off offset:64
	v_and_b32_e32 v51, 16, v51
	v_and_b32_e32 v55, 12, v55
	v_and_b32_e32 v57, 0xfffffe3, v50
	v_or3_b32 v51, v57, v51, v55
	s_movk_i32 s6, 0x120
	v_mul_lo_u32 v55, v50, s6
	v_mad_u64_u32 v[126:127], s[36:37], v51, s6, v[124:125]
	s_mov_b32 s6, 0x12000
	v_add3_u32 v127, v55, v124, s6
	v_add_u32_e32 v51, 0, v126
	v_add_u32_e32 v55, 0, v127
	s_waitcnt vmcnt(11)
	ds_write_b128 v51, v[18:21]
	s_waitcnt vmcnt(10)
	ds_write_b128 v55, v[22:25]
	s_waitcnt vmcnt(9)
	ds_write_b128 v51, v[26:29] offset:9216
	s_waitcnt vmcnt(8)
	ds_write_b128 v55, v[30:33] offset:9216
	s_waitcnt vmcnt(7)
	ds_write_b128 v51, v[34:37] offset:18432
	s_waitcnt vmcnt(6)
	ds_write_b128 v55, v[38:41] offset:18432
	s_waitcnt vmcnt(5)
	ds_write_b128 v51, v[42:45] offset:27648
	s_waitcnt vmcnt(4)
	ds_write_b128 v55, v[46:49] offset:27648
	s_add_i32 s6, 0, 0x12000
	v_mul_u32_u24_e32 v19, 0x120, v177
	v_add3_u32 v183, s6, v56, v19
	s_lshl_b32 s6, s26, 3
	s_and_b32 s6, s6, 0x700
	ds_bpermute_b32 v134, v173, v132
	ds_bpermute_b32 v135, v173, v133
	s_add_u32 s6, s42, s6
	v_add_u32_e32 v18, 0, v54
	s_addc_u32 s18, s43, 0
	v_add3_u32 v137, v18, v56, v19
	s_add_u32 s26, s6, s47
	v_mov_b64_e32 v[18:19], s[10:11]
	s_addc_u32 s27, s18, s46
	v_mad_i64_i32 v[130:131], s[10:11], v50, s35, v[18:19]
	v_mov_b32_e32 v18, 0
	s_mov_b32 s15, 0
	v_lshl_add_u64 v[128:129], s[26:27], 0, v[52:53]
	v_mov_b32_e32 v19, v18
	v_mov_b32_e32 v20, v18
	v_mov_b32_e32 v21, v18
	v_mov_b32_e32 v22, v18
	v_mov_b32_e32 v23, v18
	v_mov_b32_e32 v24, v18
	v_mov_b32_e32 v25, v18
	v_mov_b32_e32 v26, v18
	v_mov_b32_e32 v27, v18
	v_mov_b32_e32 v28, v18
	v_mov_b32_e32 v29, v18
	v_mov_b32_e32 v30, v18
	v_mov_b32_e32 v31, v18
	v_mov_b32_e32 v32, v18
	v_mov_b32_e32 v33, v18
	v_mov_b32_e32 v38, v18
	v_mov_b32_e32 v39, v18
	v_mov_b32_e32 v40, v18
	v_mov_b32_e32 v41, v18
	v_mov_b32_e32 v46, v18
	v_mov_b32_e32 v47, v18
	v_mov_b32_e32 v48, v18
	v_mov_b32_e32 v49, v18
	v_mov_b32_e32 v62, v18
	v_mov_b32_e32 v63, v18
	v_mov_b32_e32 v64, v18
	v_mov_b32_e32 v65, v18
	v_mov_b32_e32 v74, v18
	v_mov_b32_e32 v75, v18
	v_mov_b32_e32 v76, v18
	v_mov_b32_e32 v77, v18
	v_mov_b32_e32 v34, v18
	v_mov_b32_e32 v35, v18
	v_mov_b32_e32 v36, v18
	v_mov_b32_e32 v37, v18
	v_mov_b32_e32 v42, v18
	v_mov_b32_e32 v43, v18
	v_mov_b32_e32 v44, v18
	v_mov_b32_e32 v45, v18
	v_mov_b32_e32 v50, v18
	v_mov_b32_e32 v51, v18
	v_mov_b32_e32 v52, v18
	v_mov_b32_e32 v53, v18
	v_mov_b32_e32 v54, v18
	v_mov_b32_e32 v55, v18
	v_mov_b32_e32 v56, v18
	v_mov_b32_e32 v57, v18
	v_mov_b32_e32 v58, v18
	v_mov_b32_e32 v59, v18
	v_mov_b32_e32 v60, v18
	v_mov_b32_e32 v61, v18
	v_mov_b32_e32 v66, v18
	v_mov_b32_e32 v67, v18
	v_mov_b32_e32 v68, v18
	v_mov_b32_e32 v69, v18
	v_mov_b32_e32 v70, v18
	v_mov_b32_e32 v71, v18
	v_mov_b32_e32 v72, v18
	v_mov_b32_e32 v73, v18
	v_mov_b32_e32 v78, v18
	v_mov_b32_e32 v79, v18
	v_mov_b32_e32 v80, v18
	v_mov_b32_e32 v81, v18
	v_mov_b32_e32 v122, v18
	v_mov_b32_e32 v123, v18
	s_mov_b32 s11, 0xe054000
	s_mov_b32 s18, 0x16870000
	s_mov_b32 s26, 0xe098000
	s_mov_b32 s27, 0x16880000
	s_mov_b32 s30, 0xe0dc000
	s_mov_b64 s[36:37], 0x40000
	s_waitcnt lgkmcnt(0)
	s_barrier
	s_waitcnt vmcnt(0) lgkmcnt(0)
	v_writelane_b32 v175, s64, 0
	v_writelane_b32 v175, s65, 1
	v_writelane_b32 v175, s66, 2
	v_writelane_b32 v175, s67, 3
	v_writelane_b32 v175, s68, 4
	v_writelane_b32 v175, s69, 5
	v_writelane_b32 v175, s70, 6
	v_writelane_b32 v175, s71, 7
	v_writelane_b32 v175, s72, 8
	v_writelane_b32 v175, s73, 9
	v_writelane_b32 v175, s74, 10
	v_writelane_b32 v175, s75, 11
	v_writelane_b32 v175, s76, 12
	v_writelane_b32 v175, s77, 13
	v_writelane_b32 v175, s78, 14
	v_writelane_b32 v175, s79, 15
	v_lshl_add_u64 v[138:139], v[128:129], 0, v[124:125]
	v_lshl_add_u64 v[140:141], v[130:131], 0, v[124:125]
	s_nop 1
	v_readfirstlane_b32 s64, v138
	v_readfirstlane_b32 s65, v139
	v_readfirstlane_b32 s72, v140
	v_readfirstlane_b32 s73, v141
	s_nop 3
	v_subrev_u32_e32 v124, s64, v138
	v_subrev_u32_e32 v125, s72, v140
	s_add_u32 s66, s64, s97
	s_addc_u32 s67, s65, 0
	s_add_u32 s68, s64, s18
	s_addc_u32 s69, s65, 0
	s_add_u32 s70, s64, s27
	s_addc_u32 s71, s65, 0
	s_add_u32 s64, s64, s96
	s_addc_u32 s65, s65, 0
	s_add_u32 s74, s72, s11
	s_addc_u32 s75, s73, 0
	s_add_u32 s74, s74, 0x100
	s_addc_u32 s75, s75, 0
	s_add_u32 s76, s72, s26
	s_addc_u32 s77, s73, 0
	s_add_u32 s76, s76, 0x100
	s_addc_u32 s77, s77, 0
	s_add_u32 s78, s72, s30
	s_addc_u32 s79, s73, 0
	s_add_u32 s78, s78, 0x100
	s_addc_u32 s79, s79, 0
	s_add_u32 s72, s72, s91
	s_addc_u32 s73, s73, 0
	s_add_u32 s72, s72, 0x100
	s_addc_u32 s73, s73, 0
	s_mov_b32 s15, 0
	s_nop 4
	.p2align 6
